# static s_setprio 1 for waves 0-3 (older half) at every phase latch; GEMM flips untouched
# baseline (speedup 1.0000x reference)
.LBB0_18:
	v_readlane_b32 s98, v251, 7
	s_nop 3
	s_cmp_lt_u32 s98, 0x100
	s_cbranch_scc0 .Lprio_keep
	s_setprio 1
